# kernel-start fence (L2 write-back + invalidate) executed by wave 0 only and completed before the workgroup barrier
# speedup vs baseline: 1.0324x; 1.0102x over previous
.LBB0_5:
	s_or_b64 exec, exec, s[0:1]
	s_movk_i32 s0, 0x2000
	s_lshr_b32 s25, s22, 6
	v_cmp_gt_i32_e32 vcc, s0, v2
	s_cmp_lg_u32 s25, 0
	s_cbranch_scc1 .Lks_nowb
	buffer_wbl2 sc1
	s_waitcnt vmcnt(0) lgkmcnt(0)
	buffer_inv sc1
.Lks_nowb:
	s_waitcnt vmcnt(0) lgkmcnt(0)
	s_barrier
	s_and_saveexec_b64 s[0:1], vcc
	s_cbranch_execz .LBB0_8
	v_mov_b32_e32 v3, 0xf000
	global_load_dwordx2 v[4:5], v3, s[46:47] offset:8
	s_lshl_b32 s2, s25, 8
	s_add_i32 s2, s2, 16
	v_lshl_add_u32 v3, v192, 2, s2
	v_readlane_b32 s2, v252, 2
	v_mov_b32_e32 v193, 0
	v_readlane_b32 s3, v252, 3
	s_mov_b32 s4, s2
	s_ashr_i32 s5, s2, 31
	v_writelane_b32 v252, s2, 2
	v_lshl_add_u64 v[6:7], v[192:193], 0, s[4:5]
	v_add_u32_e32 v3, 0x11170, v3
	v_add_u32_e32 v8, 0xfffffe00, v2
	v_writelane_b32 v252, s3, 3
	v_lshlrev_b64 v[6:7], 2, v[6:7]
	s_mov_b64 s[2:3], 0
	s_mov_b64 s[4:5], 0x800
	s_movk_i32 s6, 0x1dff
	s_waitcnt vmcnt(0)
	v_readfirstlane_b32 s8, v4
	v_readfirstlane_b32 s9, v5
	s_nop 1
	v_lshl_add_u64 v[10:11], s[8:9], 0, v[6:7]
	global_load_dword v12, v[10:11], off
	global_load_dword v13, v[10:11], off offset:2048
	v_add_co_u32_e32 v10, vcc, 0x1000, v10
	s_nop 1
	v_addc_co_u32_e32 v11, vcc, 0, v11, vcc
	global_load_dword v14, v[10:11], off
	global_load_dword v15, v[10:11], off offset:2048
	v_add_co_u32_e32 v10, vcc, 0x1000, v10
	s_nop 1
	v_addc_co_u32_e32 v11, vcc, 0, v11, vcc
	global_load_dword v16, v[10:11], off
	global_load_dword v17, v[10:11], off offset:2048
	v_add_co_u32_e32 v10, vcc, 0x1000, v10
	s_nop 1
	v_addc_co_u32_e32 v11, vcc, 0, v11, vcc
	global_load_dword v18, v[10:11], off
	global_load_dword v19, v[10:11], off offset:2048
	v_add_co_u32_e32 v10, vcc, 0x1000, v10
	s_nop 1
	v_addc_co_u32_e32 v11, vcc, 0, v11, vcc
	global_load_dword v20, v[10:11], off
	global_load_dword v21, v[10:11], off offset:2048
	v_add_co_u32_e32 v10, vcc, 0x1000, v10
	s_nop 1
	v_addc_co_u32_e32 v11, vcc, 0, v11, vcc
	global_load_dword v22, v[10:11], off
	global_load_dword v23, v[10:11], off offset:2048
	v_add_co_u32_e32 v10, vcc, 0x1000, v10
	s_nop 1
	v_addc_co_u32_e32 v11, vcc, 0, v11, vcc
	global_load_dword v24, v[10:11], off
	global_load_dword v25, v[10:11], off offset:2048
	v_add_co_u32_e32 v10, vcc, 0x1000, v10
	s_nop 1
	v_addc_co_u32_e32 v11, vcc, 0, v11, vcc
	global_load_dword v26, v[10:11], off
	global_load_dword v27, v[10:11], off offset:2048
	s_waitcnt vmcnt(14)
	v_mul_f32_e32 v6, 0xbfb8aa3b, v12
	v_mul_f32_e32 v7, 0xbfb8aa3b, v13
	v_exp_f32_e32 v6, v6
	v_exp_f32_e32 v7, v7
	s_nop 0
	v_add_f32_e32 v6, 1.0, v6
	v_add_f32_e32 v7, 1.0, v7
	v_rcp_f32_e32 v6, v6
	v_rcp_f32_e32 v7, v7
	s_nop 0
	v_mul_f32_e32 v12, v12, v6
	v_mul_f32_e32 v13, v13, v7
	ds_write_b32 v3, v12
	ds_write_b32 v3, v13 offset:2048
	s_waitcnt vmcnt(12)
	v_mul_f32_e32 v6, 0xbfb8aa3b, v14
	v_mul_f32_e32 v7, 0xbfb8aa3b, v15
	v_exp_f32_e32 v6, v6
	v_exp_f32_e32 v7, v7
	s_nop 0
	v_add_f32_e32 v6, 1.0, v6
	v_add_f32_e32 v7, 1.0, v7
	v_rcp_f32_e32 v6, v6
	v_rcp_f32_e32 v7, v7
	s_nop 0
	v_mul_f32_e32 v14, v14, v6
	v_mul_f32_e32 v15, v15, v7
	ds_write_b32 v3, v14 offset:4096
	ds_write_b32 v3, v15 offset:6144
	s_waitcnt vmcnt(10)
	v_mul_f32_e32 v6, 0xbfb8aa3b, v16
	v_mul_f32_e32 v7, 0xbfb8aa3b, v17
	v_exp_f32_e32 v6, v6
	v_exp_f32_e32 v7, v7
	s_nop 0
	v_add_f32_e32 v6, 1.0, v6
	v_add_f32_e32 v7, 1.0, v7
	v_rcp_f32_e32 v6, v6
	v_rcp_f32_e32 v7, v7
	s_nop 0
	v_mul_f32_e32 v16, v16, v6
	v_mul_f32_e32 v17, v17, v7
	ds_write_b32 v3, v16 offset:8192
	ds_write_b32 v3, v17 offset:10240
	s_waitcnt vmcnt(8)
	v_mul_f32_e32 v6, 0xbfb8aa3b, v18
	v_mul_f32_e32 v7, 0xbfb8aa3b, v19
	v_exp_f32_e32 v6, v6
	v_exp_f32_e32 v7, v7
	s_nop 0
	v_add_f32_e32 v6, 1.0, v6
	v_add_f32_e32 v7, 1.0, v7
	v_rcp_f32_e32 v6, v6
	v_rcp_f32_e32 v7, v7
	s_nop 0
	v_mul_f32_e32 v18, v18, v6
	v_mul_f32_e32 v19, v19, v7
	ds_write_b32 v3, v18 offset:12288
	ds_write_b32 v3, v19 offset:14336
	s_waitcnt vmcnt(6)
	v_mul_f32_e32 v6, 0xbfb8aa3b, v20
	v_mul_f32_e32 v7, 0xbfb8aa3b, v21
	v_exp_f32_e32 v6, v6
	v_exp_f32_e32 v7, v7
	s_nop 0
	v_add_f32_e32 v6, 1.0, v6
	v_add_f32_e32 v7, 1.0, v7
	v_rcp_f32_e32 v6, v6
	v_rcp_f32_e32 v7, v7
	s_nop 0
	v_mul_f32_e32 v20, v20, v6
	v_mul_f32_e32 v21, v21, v7
	ds_write_b32 v3, v20 offset:16384
	ds_write_b32 v3, v21 offset:18432
	s_waitcnt vmcnt(4)
	v_mul_f32_e32 v6, 0xbfb8aa3b, v22
	v_mul_f32_e32 v7, 0xbfb8aa3b, v23
	v_exp_f32_e32 v6, v6
	v_exp_f32_e32 v7, v7
	s_nop 0
	v_add_f32_e32 v6, 1.0, v6
	v_add_f32_e32 v7, 1.0, v7
	v_rcp_f32_e32 v6, v6
	v_rcp_f32_e32 v7, v7
	s_nop 0
	v_mul_f32_e32 v22, v22, v6
	v_mul_f32_e32 v23, v23, v7
	ds_write_b32 v3, v22 offset:20480
	ds_write_b32 v3, v23 offset:22528
	s_waitcnt vmcnt(2)
	v_mul_f32_e32 v6, 0xbfb8aa3b, v24
	v_mul_f32_e32 v7, 0xbfb8aa3b, v25
	v_exp_f32_e32 v6, v6
	v_exp_f32_e32 v7, v7
	s_nop 0
	v_add_f32_e32 v6, 1.0, v6
	v_add_f32_e32 v7, 1.0, v7
	v_rcp_f32_e32 v6, v6
	v_rcp_f32_e32 v7, v7
	s_nop 0
	v_mul_f32_e32 v24, v24, v6
	v_mul_f32_e32 v25, v25, v7
	ds_write_b32 v3, v24 offset:24576
	ds_write_b32 v3, v25 offset:26624
	s_waitcnt vmcnt(0)
	v_mul_f32_e32 v6, 0xbfb8aa3b, v26
	v_mul_f32_e32 v7, 0xbfb8aa3b, v27
	v_exp_f32_e32 v6, v6
	v_exp_f32_e32 v7, v7
	s_nop 0
	v_add_f32_e32 v6, 1.0, v6
	v_add_f32_e32 v7, 1.0, v7
	v_rcp_f32_e32 v6, v6
	v_rcp_f32_e32 v7, v7
	s_nop 0
	v_mul_f32_e32 v26, v26, v6
	v_mul_f32_e32 v27, v27, v7
	ds_write_b32 v3, v26 offset:28672
	ds_write_b32 v3, v27 offset:30720
